# rwkv step loop: 2 rows x 4 keys per lane with parity-swapped pairs, 9 DPP per step; lowrank epilogue fixes
# speedup vs baseline: 1.0325x; 1.0050x over previous
.LBB0_995:
	s_or_b64 exec, exec, s[4:5]
	v_readlane_b32 s4, v252, 18
	v_readlane_b32 s5, v252, 19
	s_and_b64 vcc, exec, s[4:5]
	v_cmp_eq_u32_e64 s[8:9], 0, v211
	s_barrier
	s_cbranch_vccnz .LBB0_1019
	v_and_b32_e32 v89, 15, v156
	v_lshrrev_b32_e32 v91, 6, v156
	v_bfe_u32 v92, v156, 4, 2
	v_cmp_gt_u32_e64 s[8:9], 2, v89
	v_and_b32_e32 v93, 1, v156
	v_lshlrev_b32_e32 v89, 4, v89
	v_lshlrev_b32_e32 v91, 3, v91
	v_lshl_add_u32 v91, v92, 1, v91
	v_add_u32_e32 v91, v91, v93
	v_lshlrev_b32_e32 v91, 2, v91
	v_add_u32_e32 v131, 0xc000, v91
	v_lshl_add_u32 v143, v211, 5, 0
	s_movk_i32 s4, 0x600
	v_mad_u32_u24 v144, v157, s4, v143
	s_add_u32 s4, s94, 0x10200000
	s_addc_u32 s5, s95, 0
	v_mov_b32_e32 v133, 0
	v_lshl_add_u32 v145, v157, 2, 0
	v_lshlrev_b32_e32 v0, 2, v211
	v_mul_u32_u24_e32 v1, 0x7c, v157
	s_add_u32 s22, s94, 0x3a740000
	v_lshlrev_b32_e32 v137, 3, v211
	v_add3_u32 v146, v145, v1, v186
	s_addc_u32 s23, s95, 0
	v_add_u32_e32 v147, 0xc000, v145
	v_add_u32_e32 v148, 0xb00, v145
	v_add_u32_e32 v149, 0x600, v143
	v_lshlrev_b32_e32 v134, 1, v0
	v_mov_b32_e32 v135, v133
	s_mov_b32 s24, 0x11210000
	s_mov_b32 s25, s88
	s_branch .LBB0_998
.LBB0_997:
	s_and_b64 s[16:17], s[18:19], exec
	s_cselect_b32 s16, s24, 0x10800000
	s_add_u32 s16, s92, s16
	s_addc_u32 s17, s93, 0
	s_add_i32 s25, s25, s96
	s_cmpk_lt_i32 s25, 0x400
	v_mov_b32_e32 v92, v44
	v_mov_b32_e32 v93, v46
	v_mov_b32_e32 v94, v48
	v_mov_b32_e32 v95, v50
	v_mov_b32_e32 v96, v45
	v_mov_b32_e32 v97, v47
	v_mov_b32_e32 v98, v49
	v_mov_b32_e32 v99, v51
	v_xor_b32_e32 v100, 0x100, v150
	global_store_dwordx4 v150, v[92:95], s[16:17]
	global_store_dwordx4 v100, v[96:99], s[16:17]
	s_barrier
	s_cbranch_scc0 .LBB0_1019
.LBB0_998:
	s_and_b32 s21, s25, 15
	s_cmpk_gt_i32 s25, 0x1ff
	s_cselect_b64 s[18:19], -1, 0
	s_bfe_u32 s16, s25, 0x40004
	s_bfe_u32 s20, s25, 0x10008
	s_lshl_b32 s26, s21, 16
	s_lshl_b32 s27, s16, 12
	s_lshl_b32 s17, s20, 5
	s_or_b32 s26, s26, s27
	s_lshl_b32 s27, s26, 2
	v_lshl_add_u32 v90, s17, 2, v91
	v_lshl_add_u32 v150, v90, 6, v89
	v_add_u32_e32 v150, s27, v150
	v_xor_b32_e32 v100, 0x100, v150
	v_mov_b32_e32 v132, v133
	s_cmpk_lt_i32 s25, 0x200
	s_waitcnt vmcnt(0)
	v_mov_b64_e32 v[92:93], v[132:133]
	v_mov_b64_e32 v[94:95], v[132:133]
	v_mov_b64_e32 v[96:97], v[132:133]
	v_mov_b64_e32 v[98:99], v[132:133]
	s_cbranch_scc1 .LBB0_1000
	v_readlane_b32 s72, v253, 0
	v_readlane_b32 s80, v253, 8
	v_readlane_b32 s81, v253, 9
	s_nop 4
	global_load_dwordx4 v[92:95], v150, s[80:81]
	global_load_dwordx4 v[96:99], v100, s[80:81]
	v_readlane_b32 s73, v253, 1
	v_readlane_b32 s74, v253, 2
	v_readlane_b32 s75, v253, 3
	v_readlane_b32 s76, v253, 4
	v_readlane_b32 s77, v253, 5
	v_readlane_b32 s78, v253, 6
	v_readlane_b32 s79, v253, 7
	v_readlane_b32 s82, v253, 10
	v_readlane_b32 s83, v253, 11
	v_readlane_b32 s84, v253, 12
	v_readlane_b32 s85, v253, 13
	v_readlane_b32 s86, v253, 14
	v_readlane_b32 s87, v253, 15
.LBB0_1000:
	s_lshr_b32 s26, s25, 8
	s_and_b32 s28, s26, 1
	s_and_b64 s[26:27], s[18:19], exec
	s_cselect_b32 s26, 16, 0
	s_or_b32 s21, s26, s21
	s_lshl_b32 s29, s21, 12
	s_lshl_b32 s21, s21, 5
	s_add_i32 s21, s21, 0xfe00
	s_and_b64 s[26:27], s[18:19], exec
	v_lshl_or_b32 v136, s16, 6, v137
	v_readlane_b32 s72, v253, 42
	s_cselect_b32 s21, s21, s29
	v_lshlrev_b32_e32 v20, 2, v136
	v_readlane_b32 s73, v253, 43
	v_readlane_b32 s74, v253, 44
	v_readlane_b32 s75, v253, 45
	v_readlane_b32 s76, v253, 46
	v_readlane_b32 s77, v253, 47
	v_readlane_b32 s78, v253, 48
	v_readlane_b32 s79, v253, 49
	v_readlane_b32 s80, v253, 50
	v_readlane_b32 s81, v253, 51
	v_readlane_b32 s82, v253, 52
	v_readlane_b32 s83, v253, 53
	v_readlane_b32 s84, v253, 54
	v_readlane_b32 s85, v253, 55
	v_readlane_b32 s86, v253, 56
	v_readlane_b32 s87, v253, 57
	s_nop 4
	global_load_dwordx4 v[0:3], v20, s[86:87] offset:16
	global_load_dwordx4 v[4:7], v20, s[86:87]
	v_readlane_b32 s72, v253, 58
	v_add_u32_e32 v151, s21, v157
	v_lshlrev_b32_e32 v24, 1, v136
	v_readlane_b32 s74, v253, 60
	v_readlane_b32 s75, v253, 61
	v_lshl_or_b32 v40, v151, 11, v24
	v_readlane_b32 s73, v253, 59
	s_nop 2
	global_load_dwordx4 v[8:11], v20, s[74:75] offset:16
	s_nop 0
	global_load_dwordx4 v[12:15], v20, s[72:73] offset:16
	global_load_dwordx4 v[16:19], v20, s[74:75]
	s_nop 0
	global_load_dwordx4 v[20:23], v20, s[72:73]
	s_nop 0
	global_load_dwordx4 v[24:27], v40, s[4:5]
	global_load_dwordx4 v[32:35], v40, s[38:39]
	global_load_dwordx4 v[36:39], v40, s[2:3]
	global_load_dwordx4 v[28:31], v40, s[0:1]
	s_nop 0
	global_load_dwordx4 v[40:43], v40, s[6:7]
	s_cselect_b32 s27, 1, 0x80
	v_or_b32_e32 v52, s20, v211
	s_lshl_b32 s20, s16, 7
	s_add_u32 s20, s94, s20
	v_lshl_add_u32 v161, s17, 2, v145
	s_addc_u32 s21, s95, 0
	s_lshl_b32 s17, s17, 1
	s_add_u32 s20, s20, s17
	s_addc_u32 s21, s21, 0
	s_lshl_b32 s16, s16, 2
	v_lshl_add_u64 v[138:139], s[20:21], 0, v[134:135]
	s_add_u32 s20, s22, s16
	v_lshl_add_u32 v159, s28, 7, v148
	s_mov_b32 s26, 0
	v_cmp_eq_u32_e32 vcc, 0, v52
	s_addc_u32 s21, s23, 0
	v_readlane_b32 s76, v253, 62
	v_readlane_b32 s77, v253, 63
	v_readlane_b32 s78, v252, 0
	v_readlane_b32 s79, v252, 1
	v_readlane_b32 s80, v252, 2
	v_readlane_b32 s81, v252, 3
	v_readlane_b32 s82, v252, 4
	v_readlane_b32 s83, v252, 5
	v_readlane_b32 s84, v252, 6
	v_readlane_b32 s85, v252, 7
	v_readlane_b32 s86, v252, 8
	v_readlane_b32 s87, v252, 9
	s_barrier
	s_waitcnt vmcnt(11)
	v_mov_b32_e32 v44, v92
	v_mov_b32_e32 v45, v96
	v_mov_b32_e32 v46, v93
	v_mov_b32_e32 v47, v97
	v_mov_b32_e32 v48, v94
	v_mov_b32_e32 v49, v98
	v_mov_b32_e32 v50, v95
	v_mov_b32_e32 v51, v99
	s_branch .LBB0_1002

.LBB0_1006:
	v_mov_b32_e32 v140, v89
	v_mov_b32_e32 v141, v90
	v_xor_b32_e32 v163, 4, v90
	v_mov_b32_e32 v142, v131
	s_mov_b32 s28, 0
	ds_read_b128 v[104:107], v140 offset:768
	ds_read_b128 v[96:99], v140 offset:256
	ds_read_b128 v[100:103], v140 offset:512
	ds_read_b128 v[108:111], v140 offset:1024
	ds_read_b128 v[92:95], v140 offset:0
	ds_read_b32 v112, v141 offset:1280
	ds_read_b32 v113, v163 offset:1280
	ds_read_b128 v[64:67], v140 offset:2304
	ds_read_b128 v[56:59], v140 offset:1792
	ds_read_b128 v[60:63], v140 offset:2048
	ds_read_b128 v[68:71], v140 offset:2560
	ds_read_b128 v[52:55], v140 offset:1536
	ds_read_b32 v72, v141 offset:2816
	ds_read_b32 v73, v163 offset:2816
.Lrwkv_step4:
	s_waitcnt lgkmcnt(7)
	v_pk_mul_f32 v[74:75], v[44:45], v[104:105] op_sel:[0,0] op_sel_hi:[1,0]
	v_pk_mul_f32 v[78:79], v[44:45], v[96:97] op_sel:[0,0] op_sel_hi:[1,0]
	v_pk_fma_f32 v[74:75], v[46:47], v[104:105], v[74:75] op_sel:[0,1,0] op_sel_hi:[1,1,1]
	v_pk_mul_f32 v[80:81], v[46:47], v[96:97] op_sel:[0,1] op_sel_hi:[1,1]
	v_pk_fma_f32 v[74:75], v[48:49], v[106:107], v[74:75] op_sel:[0,0,0] op_sel_hi:[1,0,1]
	v_pk_mul_f32 v[82:83], v[48:49], v[98:99] op_sel:[0,0] op_sel_hi:[1,0]
	v_pk_fma_f32 v[74:75], v[50:51], v[106:107], v[74:75] op_sel:[0,1,0] op_sel_hi:[1,1,1]
	v_pk_mul_f32 v[84:85], v[50:51], v[98:99] op_sel:[0,1] op_sel_hi:[1,1]
	v_pk_fma_f32 v[78:79], v[100:101], v[112:113], v[78:79] op_sel:[0,0,0] op_sel_hi:[0,1,1]
	v_pk_fma_f32 v[80:81], v[100:101], v[112:113], v[80:81] op_sel:[1,0,0] op_sel_hi:[1,1,1]
	v_add_f32_dpp v74, v75, v74 quad_perm:[1,0,3,2] row_mask:0xf bank_mask:0xf bound_ctrl:1
	v_pk_fma_f32 v[82:83], v[102:103], v[112:113], v[82:83] op_sel:[0,0,0] op_sel_hi:[0,1,1]
	v_pk_fma_f32 v[84:85], v[102:103], v[112:113], v[84:85] op_sel:[1,0,0] op_sel_hi:[1,1,1]
	v_add_f32_dpp v74, v74, v74 quad_perm:[2,3,0,1] row_mask:0xf bank_mask:0xf bound_ctrl:1
	s_nop 1
	v_add_f32_dpp v74, v74, v74 row_ror:4 row_mask:0xf bank_mask:0xf bound_ctrl:1
	s_nop 1
	v_add_f32_dpp v74, v74, v74 row_ror:8 row_mask:0xf bank_mask:0xf bound_ctrl:1
	s_nop 1
	v_mov_b32_dpp v75, v74 quad_perm:[1,0,3,2] row_mask:0xf bank_mask:0xf bound_ctrl:1
	v_pk_fma_f32 v[44:45], v[108:109], v[74:75], v[78:79] op_sel:[0,0,0] op_sel_hi:[0,1,1] neg_lo:[0,1,0] neg_hi:[0,1,0]
	v_pk_fma_f32 v[46:47], v[108:109], v[74:75], v[80:81] op_sel:[1,0,0] op_sel_hi:[1,1,1] neg_lo:[0,1,0] neg_hi:[0,1,0]
	v_pk_fma_f32 v[48:49], v[110:111], v[74:75], v[82:83] op_sel:[0,0,0] op_sel_hi:[0,1,1] neg_lo:[0,1,0] neg_hi:[0,1,0]
	v_pk_fma_f32 v[50:51], v[110:111], v[74:75], v[84:85] op_sel:[1,0,0] op_sel_hi:[1,1,1] neg_lo:[0,1,0] neg_hi:[0,1,0]
	v_pk_mul_f32 v[76:77], v[44:45], v[92:93] op_sel:[0,0] op_sel_hi:[1,0]
	ds_read_b128 v[104:107], v140 offset:3840
	v_pk_fma_f32 v[76:77], v[46:47], v[92:93], v[76:77] op_sel:[0,1,0] op_sel_hi:[1,1,1]
	ds_read_b128 v[96:99], v140 offset:3328
	v_pk_fma_f32 v[76:77], v[48:49], v[94:95], v[76:77] op_sel:[0,0,0] op_sel_hi:[1,0,1]
	ds_read_b128 v[100:103], v140 offset:3584
	v_pk_fma_f32 v[76:77], v[50:51], v[94:95], v[76:77] op_sel:[0,1,0] op_sel_hi:[1,1,1]
	ds_read_b128 v[108:111], v140 offset:4096
	ds_read_b128 v[92:95], v140 offset:3072
	ds_read_b32 v112, v141 offset:4352
	ds_read_b32 v113, v163 offset:4352
	v_add_f32_dpp v76, v77, v76 quad_perm:[1,0,3,2] row_mask:0xf bank_mask:0xf bound_ctrl:1
	s_nop 1
	v_add_f32_dpp v76, v76, v76 quad_perm:[2,3,0,1] row_mask:0xf bank_mask:0xf bound_ctrl:1
	s_nop 1
	v_add_f32_dpp v76, v76, v76 row_ror:4 row_mask:0xf bank_mask:0xf bound_ctrl:1
	s_nop 1
	v_add_f32_dpp v76, v76, v76 row_ror:8 row_mask:0xf bank_mask:0xf bound_ctrl:1
	s_mov_b64 exec, s[8:9]
	ds_write_b32 v142, v76 offset:0
	s_mov_b64 exec, -1
	s_waitcnt lgkmcnt(7)
	v_pk_mul_f32 v[74:75], v[44:45], v[64:65] op_sel:[0,0] op_sel_hi:[1,0]
	v_pk_mul_f32 v[78:79], v[44:45], v[56:57] op_sel:[0,0] op_sel_hi:[1,0]
	v_pk_fma_f32 v[74:75], v[46:47], v[64:65], v[74:75] op_sel:[0,1,0] op_sel_hi:[1,1,1]
	v_pk_mul_f32 v[80:81], v[46:47], v[56:57] op_sel:[0,1] op_sel_hi:[1,1]
	v_pk_fma_f32 v[74:75], v[48:49], v[66:67], v[74:75] op_sel:[0,0,0] op_sel_hi:[1,0,1]
	v_pk_mul_f32 v[82:83], v[48:49], v[58:59] op_sel:[0,0] op_sel_hi:[1,0]
	v_pk_fma_f32 v[74:75], v[50:51], v[66:67], v[74:75] op_sel:[0,1,0] op_sel_hi:[1,1,1]
	v_pk_mul_f32 v[84:85], v[50:51], v[58:59] op_sel:[0,1] op_sel_hi:[1,1]
	v_pk_fma_f32 v[78:79], v[60:61], v[72:73], v[78:79] op_sel:[0,0,0] op_sel_hi:[0,1,1]
	v_pk_fma_f32 v[80:81], v[60:61], v[72:73], v[80:81] op_sel:[1,0,0] op_sel_hi:[1,1,1]
	v_add_f32_dpp v74, v75, v74 quad_perm:[1,0,3,2] row_mask:0xf bank_mask:0xf bound_ctrl:1
	v_pk_fma_f32 v[82:83], v[62:63], v[72:73], v[82:83] op_sel:[0,0,0] op_sel_hi:[0,1,1]
	v_pk_fma_f32 v[84:85], v[62:63], v[72:73], v[84:85] op_sel:[1,0,0] op_sel_hi:[1,1,1]
	v_add_f32_dpp v74, v74, v74 quad_perm:[2,3,0,1] row_mask:0xf bank_mask:0xf bound_ctrl:1
	s_nop 1
	v_add_f32_dpp v74, v74, v74 row_ror:4 row_mask:0xf bank_mask:0xf bound_ctrl:1
	s_nop 1
	v_add_f32_dpp v74, v74, v74 row_ror:8 row_mask:0xf bank_mask:0xf bound_ctrl:1
	s_nop 1
	v_mov_b32_dpp v75, v74 quad_perm:[1,0,3,2] row_mask:0xf bank_mask:0xf bound_ctrl:1
	v_pk_fma_f32 v[44:45], v[68:69], v[74:75], v[78:79] op_sel:[0,0,0] op_sel_hi:[0,1,1] neg_lo:[0,1,0] neg_hi:[0,1,0]
	v_pk_fma_f32 v[46:47], v[68:69], v[74:75], v[80:81] op_sel:[1,0,0] op_sel_hi:[1,1,1] neg_lo:[0,1,0] neg_hi:[0,1,0]
	v_pk_fma_f32 v[48:49], v[70:71], v[74:75], v[82:83] op_sel:[0,0,0] op_sel_hi:[0,1,1] neg_lo:[0,1,0] neg_hi:[0,1,0]
	v_pk_fma_f32 v[50:51], v[70:71], v[74:75], v[84:85] op_sel:[1,0,0] op_sel_hi:[1,1,1] neg_lo:[0,1,0] neg_hi:[0,1,0]
	v_pk_mul_f32 v[76:77], v[44:45], v[52:53] op_sel:[0,0] op_sel_hi:[1,0]
	ds_read_b128 v[64:67], v140 offset:5376
	v_pk_fma_f32 v[76:77], v[46:47], v[52:53], v[76:77] op_sel:[0,1,0] op_sel_hi:[1,1,1]
	ds_read_b128 v[56:59], v140 offset:4864
	v_pk_fma_f32 v[76:77], v[48:49], v[54:55], v[76:77] op_sel:[0,0,0] op_sel_hi:[1,0,1]
	ds_read_b128 v[60:63], v140 offset:5120
	v_pk_fma_f32 v[76:77], v[50:51], v[54:55], v[76:77] op_sel:[0,1,0] op_sel_hi:[1,1,1]
	ds_read_b128 v[68:71], v140 offset:5632
	ds_read_b128 v[52:55], v140 offset:4608
	ds_read_b32 v72, v141 offset:5888
	ds_read_b32 v73, v163 offset:5888
	v_add_f32_dpp v76, v77, v76 quad_perm:[1,0,3,2] row_mask:0xf bank_mask:0xf bound_ctrl:1
	s_nop 1
	v_add_f32_dpp v76, v76, v76 quad_perm:[2,3,0,1] row_mask:0xf bank_mask:0xf bound_ctrl:1
	s_nop 1
	v_add_f32_dpp v76, v76, v76 row_ror:4 row_mask:0xf bank_mask:0xf bound_ctrl:1
	s_nop 1
	v_add_f32_dpp v76, v76, v76 row_ror:8 row_mask:0xf bank_mask:0xf bound_ctrl:1
	s_mov_b64 exec, s[8:9]
	ds_write_b32 v142, v76 offset:128
	s_mov_b64 exec, -1
	s_waitcnt lgkmcnt(7)
	v_pk_mul_f32 v[74:75], v[44:45], v[104:105] op_sel:[0,0] op_sel_hi:[1,0]
	v_pk_mul_f32 v[78:79], v[44:45], v[96:97] op_sel:[0,0] op_sel_hi:[1,0]
	v_pk_fma_f32 v[74:75], v[46:47], v[104:105], v[74:75] op_sel:[0,1,0] op_sel_hi:[1,1,1]
	v_pk_mul_f32 v[80:81], v[46:47], v[96:97] op_sel:[0,1] op_sel_hi:[1,1]
	v_pk_fma_f32 v[74:75], v[48:49], v[106:107], v[74:75] op_sel:[0,0,0] op_sel_hi:[1,0,1]
	v_pk_mul_f32 v[82:83], v[48:49], v[98:99] op_sel:[0,0] op_sel_hi:[1,0]
	v_pk_fma_f32 v[74:75], v[50:51], v[106:107], v[74:75] op_sel:[0,1,0] op_sel_hi:[1,1,1]
	v_pk_mul_f32 v[84:85], v[50:51], v[98:99] op_sel:[0,1] op_sel_hi:[1,1]
	v_pk_fma_f32 v[78:79], v[100:101], v[112:113], v[78:79] op_sel:[0,0,0] op_sel_hi:[0,1,1]
	v_pk_fma_f32 v[80:81], v[100:101], v[112:113], v[80:81] op_sel:[1,0,0] op_sel_hi:[1,1,1]
	v_add_f32_dpp v74, v75, v74 quad_perm:[1,0,3,2] row_mask:0xf bank_mask:0xf bound_ctrl:1
	v_pk_fma_f32 v[82:83], v[102:103], v[112:113], v[82:83] op_sel:[0,0,0] op_sel_hi:[0,1,1]
	v_pk_fma_f32 v[84:85], v[102:103], v[112:113], v[84:85] op_sel:[1,0,0] op_sel_hi:[1,1,1]
	v_add_f32_dpp v74, v74, v74 quad_perm:[2,3,0,1] row_mask:0xf bank_mask:0xf bound_ctrl:1
	s_nop 1
	v_add_f32_dpp v74, v74, v74 row_ror:4 row_mask:0xf bank_mask:0xf bound_ctrl:1
	s_nop 1
	v_add_f32_dpp v74, v74, v74 row_ror:8 row_mask:0xf bank_mask:0xf bound_ctrl:1
	s_nop 1
	v_mov_b32_dpp v75, v74 quad_perm:[1,0,3,2] row_mask:0xf bank_mask:0xf bound_ctrl:1
	v_pk_fma_f32 v[44:45], v[108:109], v[74:75], v[78:79] op_sel:[0,0,0] op_sel_hi:[0,1,1] neg_lo:[0,1,0] neg_hi:[0,1,0]
	v_pk_fma_f32 v[46:47], v[108:109], v[74:75], v[80:81] op_sel:[1,0,0] op_sel_hi:[1,1,1] neg_lo:[0,1,0] neg_hi:[0,1,0]
	v_pk_fma_f32 v[48:49], v[110:111], v[74:75], v[82:83] op_sel:[0,0,0] op_sel_hi:[0,1,1] neg_lo:[0,1,0] neg_hi:[0,1,0]
	v_pk_fma_f32 v[50:51], v[110:111], v[74:75], v[84:85] op_sel:[1,0,0] op_sel_hi:[1,1,1] neg_lo:[0,1,0] neg_hi:[0,1,0]
	v_pk_mul_f32 v[76:77], v[44:45], v[92:93] op_sel:[0,0] op_sel_hi:[1,0]
	ds_read_b128 v[104:107], v140 offset:6912
	v_pk_fma_f32 v[76:77], v[46:47], v[92:93], v[76:77] op_sel:[0,1,0] op_sel_hi:[1,1,1]
	ds_read_b128 v[96:99], v140 offset:6400
	v_pk_fma_f32 v[76:77], v[48:49], v[94:95], v[76:77] op_sel:[0,0,0] op_sel_hi:[1,0,1]
	ds_read_b128 v[100:103], v140 offset:6656
	v_pk_fma_f32 v[76:77], v[50:51], v[94:95], v[76:77] op_sel:[0,1,0] op_sel_hi:[1,1,1]
	ds_read_b128 v[108:111], v140 offset:7168
	ds_read_b128 v[92:95], v140 offset:6144
	ds_read_b32 v112, v141 offset:7424
	ds_read_b32 v113, v163 offset:7424
	v_add_f32_dpp v76, v77, v76 quad_perm:[1,0,3,2] row_mask:0xf bank_mask:0xf bound_ctrl:1
	s_nop 1
	v_add_f32_dpp v76, v76, v76 quad_perm:[2,3,0,1] row_mask:0xf bank_mask:0xf bound_ctrl:1
	s_nop 1
	v_add_f32_dpp v76, v76, v76 row_ror:4 row_mask:0xf bank_mask:0xf bound_ctrl:1
	s_nop 1
	v_add_f32_dpp v76, v76, v76 row_ror:8 row_mask:0xf bank_mask:0xf bound_ctrl:1
	s_mov_b64 exec, s[8:9]
	ds_write_b32 v142, v76 offset:256
	s_mov_b64 exec, -1
	s_waitcnt lgkmcnt(7)
	v_pk_mul_f32 v[74:75], v[44:45], v[64:65] op_sel:[0,0] op_sel_hi:[1,0]
	v_pk_mul_f32 v[78:79], v[44:45], v[56:57] op_sel:[0,0] op_sel_hi:[1,0]
	v_pk_fma_f32 v[74:75], v[46:47], v[64:65], v[74:75] op_sel:[0,1,0] op_sel_hi:[1,1,1]
	v_pk_mul_f32 v[80:81], v[46:47], v[56:57] op_sel:[0,1] op_sel_hi:[1,1]
	v_pk_fma_f32 v[74:75], v[48:49], v[66:67], v[74:75] op_sel:[0,0,0] op_sel_hi:[1,0,1]
	v_pk_mul_f32 v[82:83], v[48:49], v[58:59] op_sel:[0,0] op_sel_hi:[1,0]
	v_pk_fma_f32 v[74:75], v[50:51], v[66:67], v[74:75] op_sel:[0,1,0] op_sel_hi:[1,1,1]
	v_pk_mul_f32 v[84:85], v[50:51], v[58:59] op_sel:[0,1] op_sel_hi:[1,1]
	v_pk_fma_f32 v[78:79], v[60:61], v[72:73], v[78:79] op_sel:[0,0,0] op_sel_hi:[0,1,1]
	v_pk_fma_f32 v[80:81], v[60:61], v[72:73], v[80:81] op_sel:[1,0,0] op_sel_hi:[1,1,1]
	v_add_f32_dpp v74, v75, v74 quad_perm:[1,0,3,2] row_mask:0xf bank_mask:0xf bound_ctrl:1
	v_pk_fma_f32 v[82:83], v[62:63], v[72:73], v[82:83] op_sel:[0,0,0] op_sel_hi:[0,1,1]
	v_pk_fma_f32 v[84:85], v[62:63], v[72:73], v[84:85] op_sel:[1,0,0] op_sel_hi:[1,1,1]
	v_add_f32_dpp v74, v74, v74 quad_perm:[2,3,0,1] row_mask:0xf bank_mask:0xf bound_ctrl:1
	s_nop 1
	v_add_f32_dpp v74, v74, v74 row_ror:4 row_mask:0xf bank_mask:0xf bound_ctrl:1
	s_nop 1
	v_add_f32_dpp v74, v74, v74 row_ror:8 row_mask:0xf bank_mask:0xf bound_ctrl:1
	s_nop 1
	v_mov_b32_dpp v75, v74 quad_perm:[1,0,3,2] row_mask:0xf bank_mask:0xf bound_ctrl:1
	v_pk_fma_f32 v[44:45], v[68:69], v[74:75], v[78:79] op_sel:[0,0,0] op_sel_hi:[0,1,1] neg_lo:[0,1,0] neg_hi:[0,1,0]
	v_pk_fma_f32 v[46:47], v[68:69], v[74:75], v[80:81] op_sel:[1,0,0] op_sel_hi:[1,1,1] neg_lo:[0,1,0] neg_hi:[0,1,0]
	v_pk_fma_f32 v[48:49], v[70:71], v[74:75], v[82:83] op_sel:[0,0,0] op_sel_hi:[0,1,1] neg_lo:[0,1,0] neg_hi:[0,1,0]
	v_pk_fma_f32 v[50:51], v[70:71], v[74:75], v[84:85] op_sel:[1,0,0] op_sel_hi:[1,1,1] neg_lo:[0,1,0] neg_hi:[0,1,0]
	v_pk_mul_f32 v[76:77], v[44:45], v[52:53] op_sel:[0,0] op_sel_hi:[1,0]
	ds_read_b128 v[64:67], v140 offset:8448
	v_pk_fma_f32 v[76:77], v[46:47], v[52:53], v[76:77] op_sel:[0,1,0] op_sel_hi:[1,1,1]
	ds_read_b128 v[56:59], v140 offset:7936
	v_pk_fma_f32 v[76:77], v[48:49], v[54:55], v[76:77] op_sel:[0,0,0] op_sel_hi:[1,0,1]
	ds_read_b128 v[60:63], v140 offset:8192
	v_pk_fma_f32 v[76:77], v[50:51], v[54:55], v[76:77] op_sel:[0,1,0] op_sel_hi:[1,1,1]
	ds_read_b128 v[68:71], v140 offset:8704
	ds_read_b128 v[52:55], v140 offset:7680
	ds_read_b32 v72, v141 offset:8960
	ds_read_b32 v73, v163 offset:8960
	v_add_f32_dpp v76, v77, v76 quad_perm:[1,0,3,2] row_mask:0xf bank_mask:0xf bound_ctrl:1
	s_nop 1
	v_add_f32_dpp v76, v76, v76 quad_perm:[2,3,0,1] row_mask:0xf bank_mask:0xf bound_ctrl:1
	s_nop 1
	v_add_f32_dpp v76, v76, v76 row_ror:4 row_mask:0xf bank_mask:0xf bound_ctrl:1
	s_nop 1
	v_add_f32_dpp v76, v76, v76 row_ror:8 row_mask:0xf bank_mask:0xf bound_ctrl:1
	s_mov_b64 exec, s[8:9]
	ds_write_b32 v142, v76 offset:384
	s_mov_b64 exec, -1
	s_add_i32 s28, s28, 1
	v_add_u32_e32 v140, 0x1800, v140
	v_add_u32_e32 v141, 0x1800, v141
	v_add_u32_e32 v163, 0x1800, v163
	v_add_u32_e32 v142, 0x200, v142
	s_cmp_eq_u32 s28, 8
	s_cbranch_scc0 .Lrwkv_step4
	s_waitcnt lgkmcnt(0)
	s_branch .LBB0_1001
